# hand-scheduled attn_d loops: pipelined LDS reads, ALiBi folded into MFMA C-init
# speedup vs baseline: 1.0401x; 1.0401x over previous
.LBB0_610:
	s_ashr_i32 s5, s23, 7
	s_bfe_u32 s4, s23, 0x20005
	s_mul_hi_i32 s8, s5, 0x3e00000
	s_mul_i32 s5, s5, 0x3e00000
	s_add_u32 s18, s2, s5
	s_addc_u32 s19, s17, s8
	s_lshl_b32 s5, s23, 7
	s_and_b32 s5, s5, 0xf80
	v_and_b32_e32 v64, 15, v2
	v_lshl_add_u32 v0, v3, 4, s5
	v_or_b32_e32 v66, v0, v64
	v_mov_b64_e32 v[20:21], s[18:19]
	v_mad_i64_i32 v[4:5], s[18:19], v66, s65, v[20:21]
	s_lshl_b32 s8, s4, 8
	v_bfe_u32 v65, v2, 4, 2
	v_lshl_add_u64 v[4:5], v[4:5], 0, s[8:9]
	s_mov_b64 s[18:19], 0x2200
	v_lshl_add_u64 v[132:133], v[4:5], 0, s[18:19]
	v_lshlrev_b32_e32 v0, 4, v65
	v_lshl_add_u64 v[16:17], v[132:133], 0, v[0:1]
	v_ashrrev_i32_e32 v67, 4, v2
	global_load_dwordx4 v[4:7], v[16:17], off
	global_load_dwordx4 v[8:11], v[16:17], off offset:64
	global_load_dwordx4 v[12:15], v[16:17], off offset:128
	s_nop 0
	global_load_dwordx4 v[16:19], v[16:17], off offset:192
	v_lshlrev_b32_e32 v0, 4, v2
	v_mad_i64_i32 v[20:21], s[18:19], v67, s65, v[20:21]
	v_lshl_add_u64 v[20:21], v[20:21], 0, s[8:9]
	v_and_b32_e32 v0, 0xf0, v0
	v_lshl_add_u64 v[36:37], v[20:21], 0, v[0:1]
	v_add_co_u32_e32 v24, vcc, s64, v36
	s_mov_b32 s5, 0x7e000
	s_nop 0
	v_addc_co_u32_e32 v25, vcc, 0, v37, vcc
	v_add_co_u32_e32 v32, vcc, s5, v36
	s_mov_b64 s[18:19], 0x2600
	s_waitcnt lgkmcnt(0)
	v_addc_co_u32_e32 v33, vcc, 0, v37, vcc
	global_load_dwordx4 v[20:23], v[24:25], off offset:1536
	s_nop 0
	global_load_dwordx4 v[24:27], v[24:25], off offset:2560
	s_nop 0
	global_load_dwordx4 v[28:31], v[32:33], off offset:1536
	s_nop 0
	global_load_dwordx4 v[32:35], v[32:33], off offset:2560
	v_lshl_add_u64 v[134:135], v[36:37], 0, s[18:19]
	s_mov_b64 s[18:19], 0x2a00
	v_lshl_add_u64 v[136:137], v[36:37], 0, s[18:19]
	v_mul_lo_u32 v36, v67, s21
	v_add3_u32 v169, 0, v0, v36
	v_lshlrev_b32_e32 v167, 2, v65
	s_barrier
	s_not_b32 s4, s4
	s_lshl_b32 s4, s4, 1
	v_ldexp_f32 v0, 1.0, s4
	v_lshlrev_b32_e32 v68, 3, v65
	v_mul_f32_e32 v150, 0x3fb8aa3b, v0
	v_readfirstlane_b32 s4, v3
	v_mul_u32_u24_e32 v0, 0x90, v64
	s_cmp_gt_i32 s4, 3
	s_mov_b64 s[4:5], -1
	v_lshlrev_b32_e32 v171, 1, v0
	v_lshlrev_b32_e32 v172, 1, v68
	s_waitcnt vmcnt(3)
	ds_write_b128 v169, v[20:23]
	s_waitcnt vmcnt(2)
	ds_write_b128 v169, v[24:27] offset:36864
	s_waitcnt vmcnt(1)
	ds_write_b128 v169, v[28:31] offset:9216
	s_waitcnt vmcnt(0)
	ds_write_b128 v169, v[32:35] offset:46080
	v_lshlrev_b32_e32 v38, 16, v4
	v_and_b32_e32 v39, 0xffff0000, v4
	v_lshlrev_b32_e32 v4, 16, v5
	v_and_b32_e32 v5, 0xffff0000, v5
	v_lshlrev_b32_e32 v50, 16, v16
	v_and_b32_e32 v51, 0xffff0000, v16
	v_pk_mul_f32 v[38:39], v[38:39], s[16:17] op_sel_hi:[1,0]
	v_pk_mul_f32 v[52:53], v[4:5], s[16:17] op_sel_hi:[1,0]
	v_cvt_pk_bf16_f32 v4, v38, v39
	v_pk_mul_f32 v[38:39], v[50:51], s[16:17] op_sel_hi:[1,0]
	v_sub_u32_e32 v20, v167, v66
	v_cvt_pk_bf16_f32 v16, v38, v39
	v_lshlrev_b32_e32 v38, 16, v17
	v_and_b32_e32 v39, 0xffff0000, v17
	v_pk_mul_f32 v[38:39], v[38:39], s[16:17] op_sel_hi:[1,0]
	v_cvt_f32_i32_e32 v170, v20
	v_cvt_pk_bf16_f32 v17, v38, v39
	v_lshlrev_b32_e32 v38, 16, v18
	v_and_b32_e32 v39, 0xffff0000, v18
	v_pk_mul_f32 v[38:39], v[38:39], s[16:17] op_sel_hi:[1,0]
	v_lshlrev_b32_e32 v40, 16, v6
	v_cvt_pk_bf16_f32 v18, v38, v39
	v_lshlrev_b32_e32 v38, 16, v19
	v_and_b32_e32 v39, 0xffff0000, v19
	v_pk_mul_f32 v[38:39], v[38:39], s[16:17] op_sel_hi:[1,0]
	v_and_b32_e32 v41, 0xffff0000, v6
	v_cvt_pk_bf16_f32 v19, v38, v39
	v_lshlrev_b32_e32 v38, 3, v2
	v_bfe_u32 v2, v2, 2, 2
	v_lshlrev_b32_e32 v6, 16, v7
	v_and_b32_e32 v7, 0xffff0000, v7
	v_lshlrev_b32_e32 v42, 16, v8
	v_and_b32_e32 v43, 0xffff0000, v8
	v_lshlrev_b32_e32 v8, 16, v9
	v_and_b32_e32 v9, 0xffff0000, v9
	v_lshlrev_b32_e32 v44, 16, v10
	v_and_b32_e32 v45, 0xffff0000, v10
	v_lshlrev_b32_e32 v10, 16, v11
	v_and_b32_e32 v11, 0xffff0000, v11
	v_lshlrev_b32_e32 v46, 16, v12
	v_and_b32_e32 v47, 0xffff0000, v12
	v_lshlrev_b32_e32 v12, 16, v13
	v_and_b32_e32 v13, 0xffff0000, v13
	v_lshlrev_b32_e32 v48, 16, v14
	v_and_b32_e32 v49, 0xffff0000, v14
	v_lshlrev_b32_e32 v14, 16, v15
	v_and_b32_e32 v15, 0xffff0000, v15
	v_or_b32_e32 v2, v167, v2
	v_pk_mul_f32 v[40:41], v[40:41], s[16:17] op_sel_hi:[1,0]
	v_pk_mul_f32 v[54:55], v[6:7], s[16:17] op_sel_hi:[1,0]
	v_pk_mul_f32 v[42:43], v[42:43], s[16:17] op_sel_hi:[1,0]
	v_pk_mul_f32 v[56:57], v[8:9], s[16:17] op_sel_hi:[1,0]
	v_pk_mul_f32 v[44:45], v[44:45], s[16:17] op_sel_hi:[1,0]
	v_pk_mul_f32 v[58:59], v[10:11], s[16:17] op_sel_hi:[1,0]
	v_pk_mul_f32 v[46:47], v[46:47], s[16:17] op_sel_hi:[1,0]
	v_pk_mul_f32 v[60:61], v[12:13], s[16:17] op_sel_hi:[1,0]
	v_pk_mul_f32 v[48:49], v[48:49], s[16:17] op_sel_hi:[1,0]
	v_pk_mul_f32 v[62:63], v[14:15], s[16:17] op_sel_hi:[1,0]
	v_and_b32_e32 v3, 24, v38
	v_mad_u32_u24 v2, v2, s21, 0
	v_cvt_pk_bf16_f32 v5, v52, v53
	v_cvt_pk_bf16_f32 v6, v40, v41
	v_cvt_pk_bf16_f32 v7, v54, v55
	v_cvt_pk_bf16_f32 v8, v42, v43
	v_cvt_pk_bf16_f32 v9, v56, v57
	v_cvt_pk_bf16_f32 v10, v44, v45
	v_cvt_pk_bf16_f32 v11, v58, v59
	v_cvt_pk_bf16_f32 v12, v46, v47
	v_cvt_pk_bf16_f32 v13, v60, v61
	v_cvt_pk_bf16_f32 v14, v48, v49
	v_cvt_pk_bf16_f32 v15, v62, v63
	v_add_u32_e32 v168, v2, v3
	s_waitcnt lgkmcnt(0)
	s_barrier
	s_cbranch_scc0 .Ld_groupA
	v_mov_b32_e32 v28, 0
	v_mov_b32_e32 v29, 0
	v_mov_b32_e32 v30, 0
	v_mov_b32_e32 v31, 0
	v_mov_b32_e32 v32, 0
	v_mov_b32_e32 v33, 0
	v_mov_b32_e32 v34, 0
	v_mov_b32_e32 v35, 0
	v_mov_b32_e32 v40, 0
	v_mov_b32_e32 v41, 0
	v_mov_b32_e32 v42, 0
	v_mov_b32_e32 v43, 0
	v_mov_b32_e32 v52, 0
	v_mov_b32_e32 v53, 0
	v_mov_b32_e32 v54, 0
	v_mov_b32_e32 v55, 0
	v_mov_b32_e32 v56, 0
	v_mov_b32_e32 v57, 0
	v_mov_b32_e32 v58, 0
	v_mov_b32_e32 v59, 0
	v_mov_b32_e32 v64, 0
	v_mov_b32_e32 v65, 0
	v_mov_b32_e32 v66, 0
	v_mov_b32_e32 v67, 0
	v_mov_b32_e32 v72, 0
	v_mov_b32_e32 v73, 0
	v_mov_b32_e32 v74, 0
	v_mov_b32_e32 v75, 0
	v_mov_b32_e32 v84, 0
	v_mov_b32_e32 v85, 0
	v_mov_b32_e32 v86, 0
	v_mov_b32_e32 v87, 0
	v_mov_b32_e32 v36, 0
	v_mov_b32_e32 v37, 0
	v_mov_b32_e32 v38, 0
	v_mov_b32_e32 v39, 0
	v_mov_b32_e32 v44, 0
	v_mov_b32_e32 v45, 0
	v_mov_b32_e32 v46, 0
	v_mov_b32_e32 v47, 0
	v_mov_b32_e32 v48, 0
	v_mov_b32_e32 v49, 0
	v_mov_b32_e32 v50, 0
	v_mov_b32_e32 v51, 0
	v_mov_b32_e32 v60, 0
	v_mov_b32_e32 v61, 0
	v_mov_b32_e32 v62, 0
	v_mov_b32_e32 v63, 0
	v_mov_b32_e32 v68, 0
	v_mov_b32_e32 v69, 0
	v_mov_b32_e32 v70, 0
	v_mov_b32_e32 v71, 0
	v_mov_b32_e32 v76, 0
	v_mov_b32_e32 v77, 0
	v_mov_b32_e32 v78, 0
	v_mov_b32_e32 v79, 0
	v_mov_b32_e32 v80, 0
	v_mov_b32_e32 v81, 0
	v_mov_b32_e32 v82, 0
	v_mov_b32_e32 v83, 0
	v_mov_b32_e32 v20, 0
	v_mov_b32_e32 v21, 0
	v_mov_b32_e32 v22, 0
	v_mov_b32_e32 v23, 0
	v_mov_b32_e32 v120, 0
	v_mov_b32_e32 v121, 0
	v_mov_b32_e32 v122, 0
	v_mov_b32_e32 v123, 0
	v_mov_b32_e32 v124, 0
	v_mov_b32_e32 v125, 0
	v_mov_b32_e32 v126, 0
	v_mov_b32_e32 v127, 0
	v_mov_b32_e32 v128, 0
	v_mov_b32_e32 v129, 0
	v_mov_b32_e32 v130, 0
	v_mov_b32_e32 v131, 0
	v_mov_b32_e32 v152, 0
	v_mov_b32_e32 v153, 0
	v_mov_b32_e32 v154, 0
	v_mov_b32_e32 v155, 0
	v_mov_b32_e32 v0, 0
	v_mov_b32_e32 v151, 0
	v_mov_b32_e32 v24, 0xf149f2ca
	v_mov_b32_e32 v25, 0xf149f2ca
	v_add_u32_e32 v255, v171, v172
	v_mov_b32_e32 v165, v170
	s_mov_b32 s5, 0
	s_mov_b32 s31, 0
	s_mov_b32 s38, 0
	s_mov_b32 s39, 0x4800
	s_mov_b32 s30, 0xf8000
	v_mov_b32_e32 v88, 0xff800000
	v_mov_b32_e32 v89, 0xff800000
	v_mov_b32_e32 v90, 0xff800000
	v_mov_b32_e32 v91, 0xff800000
	v_mov_b32_e32 v92, 0xff800000
	v_mov_b32_e32 v93, 0xff800000
	v_mov_b32_e32 v94, 0xff800000
	v_mov_b32_e32 v95, 0xff800000
	v_mov_b32_e32 v96, 0xff800000
	v_mov_b32_e32 v97, 0xff800000
	v_mov_b32_e32 v98, 0xff800000
	v_mov_b32_e32 v99, 0xff800000
	v_mov_b32_e32 v100, 0xff800000
	v_mov_b32_e32 v101, 0xff800000
	v_mov_b32_e32 v102, 0xff800000
	v_mov_b32_e32 v103, 0xff800000
	v_mov_b32_e32 v104, 0xff800000
	v_mov_b32_e32 v105, 0xff800000
	v_mov_b32_e32 v106, 0xff800000
	v_mov_b32_e32 v107, 0xff800000
	v_mov_b32_e32 v108, 0xff800000
	v_mov_b32_e32 v109, 0xff800000
	v_mov_b32_e32 v110, 0xff800000
	v_mov_b32_e32 v111, 0xff800000
	v_mov_b32_e32 v112, 0xff800000
	v_mov_b32_e32 v113, 0xff800000
	v_mov_b32_e32 v114, 0xff800000
	v_mov_b32_e32 v115, 0xff800000
	v_mov_b32_e32 v116, 0xff800000
	v_mov_b32_e32 v117, 0xff800000
	v_mov_b32_e32 v118, 0xff800000
	v_mov_b32_e32 v119, 0xff800000
.Ld_loopB:
	s_and_b32 s8, s5, 1
	s_mul_i32 s4, s8, 0x4800
	s_xor_b32 s8, s8, 1
	s_mul_i32 s8, s8, 0x4800
	v_add_u32_e32 v173, s4, v255
	v_add_u32_e32 v175, s8, v169
	v_add_u32_e32 v174, s31, v168
	v_add_u32_e32 v203, s38, v168
	v_add_u32_e32 v164, s39, v169
	s_mov_b32 s19, 0
	s_mov_b32 s18, s30
	v_lshl_add_u64 v[212:213], v[134:135], 0, s[18:19]
	v_lshl_add_u64 v[220:221], v[136:137], 0, s[18:19]
	s_add_u32 s18, s30, 0x7c000
	v_lshl_add_u64 v[216:217], v[134:135], 0, s[18:19]
	v_lshl_add_u64 v[224:225], v[136:137], 0, s[18:19]
	global_load_dwordx4 v[212:215], v[212:213], off
	global_load_dwordx4 v[220:223], v[220:221], off
	global_load_dwordx4 v[216:219], v[216:217], off
	global_load_dwordx4 v[224:227], v[224:225], off
	ds_read_b128 v[228:231], v173 offset:0
	ds_read_b128 v[232:235], v173 offset:64
	ds_read_b128 v[236:239], v173 offset:4608
	ds_read_b128 v[240:243], v173 offset:4672
	ds_read_b128 v[244:247], v173 offset:9216
	ds_read_b128 v[248:251], v173 offset:9280
	v_max3_f32 v26, v88, v89, v90
	v_max3_f32 v26, v26, v91, v92
	v_max3_f32 v26, v26, v93, v94
	v_max3_f32 v26, v26, v95, v96
	v_max3_f32 v26, v26, v97, v98
	v_max3_f32 v26, v26, v99, v100
	v_max3_f32 v26, v26, v101, v102
	v_max_f32_e32 v26, v26, v103
	v_mov_b32_e32 v27, v26
	s_nop 1
	v_permlane16_swap_b32_e32 v26, v27
	v_max_f32_e32 v26, v26, v27
	v_mov_b32_e32 v27, v26
	s_nop 1
	v_permlane32_swap_b32_e32 v26, v27
	v_max3_f32 v2, v24, v26, v27
	v_cmp_gt_f32_e32 vcc, v2, v24
	s_cbranch_vccz .Ld_nr_B_0
	v_sub_f32_e32 v3, v24, v2
	v_exp_f32_e32 v3, v3
	v_mov_b32_e32 v24, v2
	v_mul_f32_e32 v0, v0, v3
	v_mul_f32_e32 v28, v28, v3
	v_mul_f32_e32 v29, v29, v3
	v_mul_f32_e32 v30, v30, v3
	v_mul_f32_e32 v31, v31, v3
	v_mul_f32_e32 v32, v32, v3
	v_mul_f32_e32 v33, v33, v3
	v_mul_f32_e32 v34, v34, v3
	v_mul_f32_e32 v35, v35, v3
	v_mul_f32_e32 v40, v40, v3
	v_mul_f32_e32 v41, v41, v3
	v_mul_f32_e32 v42, v42, v3
	v_mul_f32_e32 v43, v43, v3
	v_mul_f32_e32 v52, v52, v3
	v_mul_f32_e32 v53, v53, v3
	v_mul_f32_e32 v54, v54, v3
	v_mul_f32_e32 v55, v55, v3
	v_mul_f32_e32 v56, v56, v3
	v_mul_f32_e32 v57, v57, v3
	v_mul_f32_e32 v58, v58, v3
	v_mul_f32_e32 v59, v59, v3
	v_mul_f32_e32 v64, v64, v3
	v_mul_f32_e32 v65, v65, v3
	v_mul_f32_e32 v66, v66, v3
	v_mul_f32_e32 v67, v67, v3
	v_mul_f32_e32 v72, v72, v3
	v_mul_f32_e32 v73, v73, v3
	v_mul_f32_e32 v74, v74, v3
	v_mul_f32_e32 v75, v75, v3
	v_mul_f32_e32 v84, v84, v3
	v_mul_f32_e32 v85, v85, v3
	v_mul_f32_e32 v86, v86, v3
	v_mul_f32_e32 v87, v87, v3
.Ld_nr_B_0:
	v_sub_f32_e32 v88, v88, v2
	v_sub_f32_e32 v89, v89, v2
	v_sub_f32_e32 v90, v90, v2
	v_sub_f32_e32 v91, v91, v2
	v_sub_f32_e32 v92, v92, v2
	v_sub_f32_e32 v93, v93, v2
	v_sub_f32_e32 v94, v94, v2
	v_sub_f32_e32 v95, v95, v2
	v_sub_f32_e32 v96, v96, v2
	v_sub_f32_e32 v97, v97, v2
	v_sub_f32_e32 v98, v98, v2
	v_sub_f32_e32 v99, v99, v2
	v_sub_f32_e32 v100, v100, v2
	v_sub_f32_e32 v101, v101, v2
	v_sub_f32_e32 v102, v102, v2
	v_sub_f32_e32 v103, v103, v2
	v_exp_f32_e32 v88, v88
	v_exp_f32_e32 v89, v89
	v_exp_f32_e32 v90, v90
	v_exp_f32_e32 v91, v91
	v_exp_f32_e32 v92, v92
	v_exp_f32_e32 v93, v93
	v_exp_f32_e32 v94, v94
	v_exp_f32_e32 v95, v95
	v_exp_f32_e32 v96, v96
	v_exp_f32_e32 v97, v97
	v_exp_f32_e32 v98, v98
	v_exp_f32_e32 v99, v99
	v_exp_f32_e32 v100, v100
	v_exp_f32_e32 v101, v101
	v_exp_f32_e32 v102, v102
	v_exp_f32_e32 v103, v103
	s_nop 0
	v_add_f32_e32 v26, v88, v89
	v_add_f32_e32 v26, v26, v90
	v_add_f32_e32 v26, v26, v91
	v_add_f32_e32 v26, v26, v92
	v_add_f32_e32 v26, v26, v93
	v_add_f32_e32 v26, v26, v94
	v_add_f32_e32 v26, v26, v95
	v_add_f32_e32 v26, v26, v96
	v_add_f32_e32 v26, v26, v97
	v_add_f32_e32 v26, v26, v98
	v_add_f32_e32 v26, v26, v99
	v_add_f32_e32 v26, v26, v100
	v_add_f32_e32 v26, v26, v101
	v_add_f32_e32 v26, v26, v102
	v_add_f32_e32 v26, v26, v103
	v_add_f32_e32 v0, v0, v26
	v_cvt_pk_bf16_f32 v120, v88, v89
	v_cvt_pk_bf16_f32 v121, v90, v91
	v_cvt_pk_bf16_f32 v122, v92, v93
	v_cvt_pk_bf16_f32 v123, v94, v95
	v_cvt_pk_bf16_f32 v124, v96, v97
	v_cvt_pk_bf16_f32 v125, v98, v99
	v_cvt_pk_bf16_f32 v126, v100, v101
	v_cvt_pk_bf16_f32 v127, v102, v103
	v_max3_f32 v26, v104, v105, v106
	v_max3_f32 v26, v26, v107, v108
	v_max3_f32 v26, v26, v109, v110
	v_max3_f32 v26, v26, v111, v112
	v_max3_f32 v26, v26, v113, v114
	v_max3_f32 v26, v26, v115, v116
	v_max3_f32 v26, v26, v117, v118
	v_max_f32_e32 v26, v26, v119
	v_mov_b32_e32 v27, v26
	s_nop 1
	v_permlane16_swap_b32_e32 v26, v27
	v_max_f32_e32 v26, v26, v27
	v_mov_b32_e32 v27, v26
	s_nop 1
	v_permlane32_swap_b32_e32 v26, v27
	v_max3_f32 v2, v25, v26, v27
	v_cmp_gt_f32_e32 vcc, v2, v25
	s_cbranch_vccz .Ld_nr_B_1
	v_sub_f32_e32 v3, v25, v2
	v_exp_f32_e32 v3, v3
	v_mov_b32_e32 v25, v2
	v_mul_f32_e32 v151, v151, v3
	v_mul_f32_e32 v36, v36, v3
	v_mul_f32_e32 v37, v37, v3
	v_mul_f32_e32 v38, v38, v3
	v_mul_f32_e32 v39, v39, v3
	v_mul_f32_e32 v44, v44, v3
	v_mul_f32_e32 v45, v45, v3
	v_mul_f32_e32 v46, v46, v3
	v_mul_f32_e32 v47, v47, v3
	v_mul_f32_e32 v48, v48, v3
	v_mul_f32_e32 v49, v49, v3
	v_mul_f32_e32 v50, v50, v3
	v_mul_f32_e32 v51, v51, v3
	v_mul_f32_e32 v60, v60, v3
	v_mul_f32_e32 v61, v61, v3
	v_mul_f32_e32 v62, v62, v3
	v_mul_f32_e32 v63, v63, v3
	v_mul_f32_e32 v68, v68, v3
	v_mul_f32_e32 v69, v69, v3
	v_mul_f32_e32 v70, v70, v3
	v_mul_f32_e32 v71, v71, v3
	v_mul_f32_e32 v76, v76, v3
	v_mul_f32_e32 v77, v77, v3
	v_mul_f32_e32 v78, v78, v3
	v_mul_f32_e32 v79, v79, v3
	v_mul_f32_e32 v80, v80, v3
	v_mul_f32_e32 v81, v81, v3
	v_mul_f32_e32 v82, v82, v3
	v_mul_f32_e32 v83, v83, v3
	v_mul_f32_e32 v20, v20, v3
	v_mul_f32_e32 v21, v21, v3
	v_mul_f32_e32 v22, v22, v3
	v_mul_f32_e32 v23, v23, v3
.Ld_nr_B_1:
	v_sub_f32_e32 v104, v104, v2
	v_sub_f32_e32 v105, v105, v2
	v_sub_f32_e32 v106, v106, v2
	v_sub_f32_e32 v107, v107, v2
	v_sub_f32_e32 v108, v108, v2
	v_sub_f32_e32 v109, v109, v2
	v_sub_f32_e32 v110, v110, v2
	v_sub_f32_e32 v111, v111, v2
	v_sub_f32_e32 v112, v112, v2
	v_sub_f32_e32 v113, v113, v2
	v_sub_f32_e32 v114, v114, v2
	v_sub_f32_e32 v115, v115, v2
	v_sub_f32_e32 v116, v116, v2
	v_sub_f32_e32 v117, v117, v2
	v_sub_f32_e32 v118, v118, v2
	v_sub_f32_e32 v119, v119, v2
	v_exp_f32_e32 v104, v104
	v_exp_f32_e32 v105, v105
	v_exp_f32_e32 v106, v106
	v_exp_f32_e32 v107, v107
	v_exp_f32_e32 v108, v108
	v_exp_f32_e32 v109, v109
	v_exp_f32_e32 v110, v110
	v_exp_f32_e32 v111, v111
	v_exp_f32_e32 v112, v112
	v_exp_f32_e32 v113, v113
	v_exp_f32_e32 v114, v114
	v_exp_f32_e32 v115, v115
	v_exp_f32_e32 v116, v116
	v_exp_f32_e32 v117, v117
	v_exp_f32_e32 v118, v118
	v_exp_f32_e32 v119, v119
	s_nop 0
	v_add_f32_e32 v26, v104, v105
	v_add_f32_e32 v26, v26, v106
	v_add_f32_e32 v26, v26, v107
	v_add_f32_e32 v26, v26, v108
	v_add_f32_e32 v26, v26, v109
	v_add_f32_e32 v26, v26, v110
	v_add_f32_e32 v26, v26, v111
	v_add_f32_e32 v26, v26, v112
	v_add_f32_e32 v26, v26, v113
	v_add_f32_e32 v26, v26, v114
	v_add_f32_e32 v26, v26, v115
	v_add_f32_e32 v26, v26, v116
	v_add_f32_e32 v26, v26, v117
	v_add_f32_e32 v26, v26, v118
	v_add_f32_e32 v26, v26, v119
	v_add_f32_e32 v151, v151, v26
	v_cvt_pk_bf16_f32 v128, v104, v105
	v_cvt_pk_bf16_f32 v129, v106, v107
	v_cvt_pk_bf16_f32 v130, v108, v109
	v_cvt_pk_bf16_f32 v131, v110, v111
	v_cvt_pk_bf16_f32 v152, v112, v113
	v_cvt_pk_bf16_f32 v153, v114, v115
	v_cvt_pk_bf16_f32 v154, v116, v117
	v_cvt_pk_bf16_f32 v155, v118, v119
	v_mul_f32_e64 v156, -|v165|, v150
	v_add_f32_e32 v157, 0x3f800000, v165
	v_add_f32_e32 v158, 0x40000000, v165
	v_add_f32_e32 v159, 0x40400000, v165
	v_add_f32_e32 v160, 0x41800000, v165
	v_add_f32_e32 v161, 0x41880000, v165
	v_add_f32_e32 v162, 0x41900000, v165
	v_add_f32_e32 v163, 0x41980000, v165
	v_add_f32_e32 v176, 0x42000000, v165
	v_add_f32_e32 v177, 0x42040000, v165
	v_add_f32_e32 v178, 0x42080000, v165
	v_add_f32_e32 v179, 0x420c0000, v165
	v_add_f32_e32 v180, 0x42400000, v165
	v_add_f32_e32 v181, 0x42440000, v165
	v_add_f32_e32 v182, 0x42480000, v165
	v_add_f32_e32 v183, 0x424c0000, v165
	v_mul_f32_e64 v157, -|v157|, v150
	v_mul_f32_e64 v158, -|v158|, v150
	v_mul_f32_e64 v159, -|v159|, v150
	v_mul_f32_e64 v160, -|v160|, v150
	v_mul_f32_e64 v161, -|v161|, v150
	v_mul_f32_e64 v162, -|v162|, v150
	v_mul_f32_e64 v163, -|v163|, v150
	v_mul_f32_e64 v176, -|v176|, v150
	v_mul_f32_e64 v177, -|v177|, v150
	v_mul_f32_e64 v178, -|v178|, v150
	v_mul_f32_e64 v179, -|v179|, v150
	v_mul_f32_e64 v180, -|v180|, v150
	v_mul_f32_e64 v181, -|v181|, v150
	v_mul_f32_e64 v182, -|v182|, v150
	v_mul_f32_e64 v183, -|v183|, v150
	ds_read_b128 v[184:187], v173 offset:13824
	s_waitcnt lgkmcnt(6)
	v_mfma_f32_16x16x32_bf16 v[88:91], v[228:231], v[4:7], v[156:159]
	ds_read_b128 v[188:191], v173 offset:13888
	s_waitcnt lgkmcnt(6)
	v_mfma_f32_16x16x32_bf16 v[88:91], v[232:235], v[8:11], v[88:91]
	ds_read_b128 v[204:207], v173 offset:128
	s_waitcnt lgkmcnt(6)
	v_mfma_f32_16x16x32_bf16 v[92:95], v[236:239], v[4:7], v[160:163]
	ds_read_b128 v[208:211], v173 offset:192
	s_waitcnt lgkmcnt(6)
	v_mfma_f32_16x16x32_bf16 v[92:95], v[240:243], v[8:11], v[92:95]
	ds_read_b128 v[228:231], v173 offset:4736
	s_waitcnt lgkmcnt(6)
	v_mfma_f32_16x16x32_bf16 v[96:99], v[244:247], v[4:7], v[176:179]
	ds_read_b128 v[232:235], v173 offset:4800
	s_waitcnt lgkmcnt(6)
	v_mfma_f32_16x16x32_bf16 v[96:99], v[248:251], v[8:11], v[96:99]
	ds_read_b128 v[236:239], v173 offset:9344
	s_waitcnt lgkmcnt(6)
	v_mfma_f32_16x16x32_bf16 v[100:103], v[184:187], v[4:7], v[180:183]
	ds_read_b128 v[240:243], v173 offset:9408
	s_waitcnt lgkmcnt(6)
	v_mfma_f32_16x16x32_bf16 v[100:103], v[188:191], v[8:11], v[100:103]
	ds_read_b128 v[244:247], v173 offset:13952
	s_waitcnt lgkmcnt(6)
	v_mfma_f32_16x16x32_bf16 v[104:107], v[204:207], v[12:15], v[156:159]
	ds_read_b128 v[248:251], v173 offset:14016
	s_waitcnt lgkmcnt(6)
	v_mfma_f32_16x16x32_bf16 v[104:107], v[208:211], v[16:19], v[104:107]
	ds_read_b64_tr_b16 v[184:185], v174 offset:36864
	ds_read_b64_tr_b16 v[186:187], v174 offset:41472
	s_waitcnt lgkmcnt(7)
	v_mfma_f32_16x16x32_bf16 v[108:111], v[228:231], v[12:15], v[160:163]
	ds_read_b64_tr_b16 v[188:189], v174 offset:36896
	ds_read_b64_tr_b16 v[190:191], v174 offset:41504
	s_waitcnt lgkmcnt(8)
	v_mfma_f32_16x16x32_bf16 v[108:111], v[232:235], v[16:19], v[108:111]
	ds_read_b64_tr_b16 v[204:205], v174 offset:36928
	ds_read_b64_tr_b16 v[206:207], v174 offset:41536
	s_waitcnt lgkmcnt(9)
	v_mfma_f32_16x16x32_bf16 v[112:115], v[236:239], v[12:15], v[176:179]
	ds_read_b64_tr_b16 v[208:209], v174 offset:36960
	ds_read_b64_tr_b16 v[210:211], v174 offset:41568
	s_waitcnt lgkmcnt(10)
	v_mfma_f32_16x16x32_bf16 v[112:115], v[240:243], v[16:19], v[112:115]
	ds_read_b64_tr_b16 v[228:229], v174 offset:36992
	ds_read_b64_tr_b16 v[230:231], v174 offset:41600
	s_waitcnt lgkmcnt(11)
	v_mfma_f32_16x16x32_bf16 v[116:119], v[244:247], v[12:15], v[180:183]
	ds_read_b64_tr_b16 v[232:233], v174 offset:37024
	ds_read_b64_tr_b16 v[234:235], v174 offset:41632
	s_waitcnt lgkmcnt(12)
	v_mfma_f32_16x16x32_bf16 v[116:119], v[248:251], v[16:19], v[116:119]
	ds_read_b64_tr_b16 v[236:237], v174 offset:37056
	ds_read_b64_tr_b16 v[238:239], v174 offset:41664
	s_waitcnt lgkmcnt(12)
	v_mfma_f32_16x16x32_bf16 v[28:31], v[184:187], v[120:123], v[28:31]
	v_mfma_f32_16x16x32_bf16 v[36:39], v[184:187], v[128:131], v[36:39]
	ds_read_b64_tr_b16 v[240:241], v174 offset:37088
	ds_read_b64_tr_b16 v[242:243], v174 offset:41696
	s_waitcnt lgkmcnt(12)
	v_mfma_f32_16x16x32_bf16 v[32:35], v[188:191], v[120:123], v[32:35]
	v_mfma_f32_16x16x32_bf16 v[44:47], v[188:191], v[128:131], v[44:47]
	ds_read_b64_tr_b16 v[244:245], v174 offset:46080
	ds_read_b64_tr_b16 v[246:247], v174 offset:50688
	s_waitcnt lgkmcnt(12)
	v_mfma_f32_16x16x32_bf16 v[40:43], v[204:207], v[120:123], v[40:43]
	v_mfma_f32_16x16x32_bf16 v[48:51], v[204:207], v[128:131], v[48:51]
	ds_read_b64_tr_b16 v[248:249], v174 offset:46112
	ds_read_b64_tr_b16 v[250:251], v174 offset:50720
	s_waitcnt lgkmcnt(12)
	v_mfma_f32_16x16x32_bf16 v[52:55], v[208:211], v[120:123], v[52:55]
	v_mfma_f32_16x16x32_bf16 v[60:63], v[208:211], v[128:131], v[60:63]
	ds_read_b64_tr_b16 v[184:185], v174 offset:46144
	ds_read_b64_tr_b16 v[186:187], v174 offset:50752
	s_waitcnt lgkmcnt(12)
	v_mfma_f32_16x16x32_bf16 v[56:59], v[228:231], v[120:123], v[56:59]
	v_mfma_f32_16x16x32_bf16 v[68:71], v[228:231], v[128:131], v[68:71]
	ds_read_b64_tr_b16 v[188:189], v174 offset:46176
	ds_read_b64_tr_b16 v[190:191], v174 offset:50784
	s_waitcnt lgkmcnt(12)
	v_mfma_f32_16x16x32_bf16 v[64:67], v[232:235], v[120:123], v[64:67]
	v_mfma_f32_16x16x32_bf16 v[76:79], v[232:235], v[128:131], v[76:79]
	ds_read_b64_tr_b16 v[204:205], v174 offset:46208
	ds_read_b64_tr_b16 v[206:207], v174 offset:50816
	s_waitcnt lgkmcnt(12)
	v_mfma_f32_16x16x32_bf16 v[72:75], v[236:239], v[120:123], v[72:75]
	v_mfma_f32_16x16x32_bf16 v[80:83], v[236:239], v[128:131], v[80:83]
	ds_read_b64_tr_b16 v[208:209], v174 offset:46240
	ds_read_b64_tr_b16 v[210:211], v174 offset:50848
	s_waitcnt lgkmcnt(12)
	v_mfma_f32_16x16x32_bf16 v[84:87], v[240:243], v[120:123], v[84:87]
	v_mfma_f32_16x16x32_bf16 v[20:23], v[240:243], v[128:131], v[20:23]
	ds_read_b64_tr_b16 v[228:229], v174 offset:46272
	ds_read_b64_tr_b16 v[230:231], v174 offset:50880
	s_waitcnt lgkmcnt(12)
	v_mfma_f32_16x16x32_bf16 v[28:31], v[244:247], v[124:127], v[28:31]
	v_mfma_f32_16x16x32_bf16 v[36:39], v[244:247], v[152:155], v[36:39]
	ds_read_b64_tr_b16 v[232:233], v174 offset:46304
	ds_read_b64_tr_b16 v[234:235], v174 offset:50912
	s_waitcnt lgkmcnt(12)
	v_mfma_f32_16x16x32_bf16 v[32:35], v[248:251], v[124:127], v[32:35]
	v_mfma_f32_16x16x32_bf16 v[44:47], v[248:251], v[152:155], v[44:47]
	s_waitcnt lgkmcnt(10)
	v_mfma_f32_16x16x32_bf16 v[40:43], v[184:187], v[124:127], v[40:43]
	v_mfma_f32_16x16x32_bf16 v[48:51], v[184:187], v[152:155], v[48:51]
	s_waitcnt lgkmcnt(8)
	v_mfma_f32_16x16x32_bf16 v[52:55], v[188:191], v[124:127], v[52:55]
	v_mfma_f32_16x16x32_bf16 v[60:63], v[188:191], v[152:155], v[60:63]
	s_waitcnt lgkmcnt(6)
	v_mfma_f32_16x16x32_bf16 v[56:59], v[204:207], v[124:127], v[56:59]
	v_mfma_f32_16x16x32_bf16 v[68:71], v[204:207], v[152:155], v[68:71]
	s_waitcnt lgkmcnt(4)
	v_mfma_f32_16x16x32_bf16 v[64:67], v[208:211], v[124:127], v[64:67]
	v_mfma_f32_16x16x32_bf16 v[76:79], v[208:211], v[152:155], v[76:79]
	s_waitcnt lgkmcnt(2)
	v_mfma_f32_16x16x32_bf16 v[72:75], v[228:231], v[124:127], v[72:75]
	v_mfma_f32_16x16x32_bf16 v[80:83], v[228:231], v[152:155], v[80:83]
	s_waitcnt lgkmcnt(0)
	v_mfma_f32_16x16x32_bf16 v[84:87], v[232:235], v[124:127], v[84:87]
	v_mfma_f32_16x16x32_bf16 v[20:23], v[232:235], v[152:155], v[20:23]
	s_waitcnt vmcnt(0)
	ds_write_b128 v175, v[212:215]
	ds_write_b128 v175, v[216:219] offset:9216
	ds_write_b128 v164, v[220:223] offset:36864
	ds_write_b128 v164, v[224:227] offset:46080
	s_mov_b32 s31, s38
	s_mov_b32 s38, s39
	s_add_i32 s39, s39, 0x4800
	s_cmp_lg_u32 s39, 0xd800
	s_cselect_b32 s39, s39, 0
	s_add_i32 s5, s5, 1
	s_min_u32 s8, s5, 62
	s_add_i32 s8, s8, 1
	s_mul_i32 s30, s8, 0xf8000
	v_add_f32_e32 v165, 0x42800000, v165
	s_waitcnt lgkmcnt(0)
	s_barrier
	s_cmp_lt_u32 s5, 64
	s_cbranch_scc1 .Ld_loopB
	v_add_u32_e32 v174, s31, v168
	ds_read_b64_tr_b16 v[228:229], v174 offset:36864
	ds_read_b64_tr_b16 v[230:231], v174 offset:41472
	ds_read_b64_tr_b16 v[232:233], v174 offset:36896
	ds_read_b64_tr_b16 v[234:235], v174 offset:41504
	ds_read_b64_tr_b16 v[236:237], v174 offset:36928
	ds_read_b64_tr_b16 v[238:239], v174 offset:41536
	ds_read_b64_tr_b16 v[240:241], v174 offset:36960
	ds_read_b64_tr_b16 v[242:243], v174 offset:41568
	ds_read_b64_tr_b16 v[244:245], v174 offset:36992
	ds_read_b64_tr_b16 v[246:247], v174 offset:41600
	ds_read_b64_tr_b16 v[248:249], v174 offset:37024
	ds_read_b64_tr_b16 v[250:251], v174 offset:41632
	v_max3_f32 v26, v88, v89, v90
	v_max3_f32 v26, v26, v91, v92
	v_max3_f32 v26, v26, v93, v94
	v_max3_f32 v26, v26, v95, v96
	v_max3_f32 v26, v26, v97, v98
	v_max3_f32 v26, v26, v99, v100
	v_max3_f32 v26, v26, v101, v102
	v_max_f32_e32 v26, v26, v103
	v_mov_b32_e32 v27, v26
	s_nop 1
	v_permlane16_swap_b32_e32 v26, v27
	v_max_f32_e32 v26, v26, v27
	v_mov_b32_e32 v27, v26
	s_nop 1
	v_permlane32_swap_b32_e32 v26, v27
	v_max3_f32 v2, v24, v26, v27
	v_cmp_gt_f32_e32 vcc, v2, v24
	s_cbranch_vccz .Ld_nr_Bt_0
	v_sub_f32_e32 v3, v24, v2
	v_exp_f32_e32 v3, v3
	v_mov_b32_e32 v24, v2
	v_mul_f32_e32 v0, v0, v3
	v_mul_f32_e32 v28, v28, v3
	v_mul_f32_e32 v29, v29, v3
	v_mul_f32_e32 v30, v30, v3
	v_mul_f32_e32 v31, v31, v3
	v_mul_f32_e32 v32, v32, v3
	v_mul_f32_e32 v33, v33, v3
	v_mul_f32_e32 v34, v34, v3
	v_mul_f32_e32 v35, v35, v3
	v_mul_f32_e32 v40, v40, v3
	v_mul_f32_e32 v41, v41, v3
	v_mul_f32_e32 v42, v42, v3
	v_mul_f32_e32 v43, v43, v3
	v_mul_f32_e32 v52, v52, v3
	v_mul_f32_e32 v53, v53, v3
	v_mul_f32_e32 v54, v54, v3
	v_mul_f32_e32 v55, v55, v3
	v_mul_f32_e32 v56, v56, v3
	v_mul_f32_e32 v57, v57, v3
	v_mul_f32_e32 v58, v58, v3
	v_mul_f32_e32 v59, v59, v3
	v_mul_f32_e32 v64, v64, v3
	v_mul_f32_e32 v65, v65, v3
	v_mul_f32_e32 v66, v66, v3
	v_mul_f32_e32 v67, v67, v3
	v_mul_f32_e32 v72, v72, v3
	v_mul_f32_e32 v73, v73, v3
	v_mul_f32_e32 v74, v74, v3
	v_mul_f32_e32 v75, v75, v3
	v_mul_f32_e32 v84, v84, v3
	v_mul_f32_e32 v85, v85, v3
	v_mul_f32_e32 v86, v86, v3
	v_mul_f32_e32 v87, v87, v3

.Ld_nr_Bt_1:
	v_sub_f32_e32 v104, v104, v2
	v_sub_f32_e32 v105, v105, v2
	v_sub_f32_e32 v106, v106, v2
	v_sub_f32_e32 v107, v107, v2
	v_sub_f32_e32 v108, v108, v2
	v_sub_f32_e32 v109, v109, v2
	v_sub_f32_e32 v110, v110, v2
	v_sub_f32_e32 v111, v111, v2
	v_sub_f32_e32 v112, v112, v2
	v_sub_f32_e32 v113, v113, v2
	v_sub_f32_e32 v114, v114, v2
	v_sub_f32_e32 v115, v115, v2
	v_sub_f32_e32 v116, v116, v2
	v_sub_f32_e32 v117, v117, v2
	v_sub_f32_e32 v118, v118, v2
	v_sub_f32_e32 v119, v119, v2
	v_exp_f32_e32 v104, v104
	v_exp_f32_e32 v105, v105
	v_exp_f32_e32 v106, v106
	v_exp_f32_e32 v107, v107
	v_exp_f32_e32 v108, v108
	v_exp_f32_e32 v109, v109
	v_exp_f32_e32 v110, v110
	v_exp_f32_e32 v111, v111
	v_exp_f32_e32 v112, v112
	v_exp_f32_e32 v113, v113
	v_exp_f32_e32 v114, v114
	v_exp_f32_e32 v115, v115
	v_exp_f32_e32 v116, v116
	v_exp_f32_e32 v117, v117
	v_exp_f32_e32 v118, v118
	v_exp_f32_e32 v119, v119
	s_nop 0
	v_add_f32_e32 v26, v104, v105
	v_add_f32_e32 v26, v26, v106
	v_add_f32_e32 v26, v26, v107
	v_add_f32_e32 v26, v26, v108
	v_add_f32_e32 v26, v26, v109
	v_add_f32_e32 v26, v26, v110
	v_add_f32_e32 v26, v26, v111
	v_add_f32_e32 v26, v26, v112
	v_add_f32_e32 v26, v26, v113
	v_add_f32_e32 v26, v26, v114
	v_add_f32_e32 v26, v26, v115
	v_add_f32_e32 v26, v26, v116
	v_add_f32_e32 v26, v26, v117
	v_add_f32_e32 v26, v26, v118
	v_add_f32_e32 v26, v26, v119
	v_add_f32_e32 v151, v151, v26
	v_cvt_pk_bf16_f32 v128, v104, v105
	v_cvt_pk_bf16_f32 v129, v106, v107
	v_cvt_pk_bf16_f32 v130, v108, v109
	v_cvt_pk_bf16_f32 v131, v110, v111
	v_cvt_pk_bf16_f32 v152, v112, v113
	v_cvt_pk_bf16_f32 v153, v114, v115
	v_cvt_pk_bf16_f32 v154, v116, v117
	v_cvt_pk_bf16_f32 v155, v118, v119
	ds_read_b64_tr_b16 v[184:185], v174 offset:37056
	ds_read_b64_tr_b16 v[186:187], v174 offset:41664
	s_waitcnt lgkmcnt(12)
	v_mfma_f32_16x16x32_bf16 v[28:31], v[228:231], v[120:123], v[28:31]
	v_mfma_f32_16x16x32_bf16 v[36:39], v[228:231], v[128:131], v[36:39]
	ds_read_b64_tr_b16 v[188:189], v174 offset:37088
	ds_read_b64_tr_b16 v[190:191], v174 offset:41696
	s_waitcnt lgkmcnt(12)
	v_mfma_f32_16x16x32_bf16 v[32:35], v[232:235], v[120:123], v[32:35]
	v_mfma_f32_16x16x32_bf16 v[44:47], v[232:235], v[128:131], v[44:47]
	ds_read_b64_tr_b16 v[204:205], v174 offset:46080
	ds_read_b64_tr_b16 v[206:207], v174 offset:50688
	s_waitcnt lgkmcnt(12)
	v_mfma_f32_16x16x32_bf16 v[40:43], v[236:239], v[120:123], v[40:43]
	v_mfma_f32_16x16x32_bf16 v[48:51], v[236:239], v[128:131], v[48:51]
	ds_read_b64_tr_b16 v[208:209], v174 offset:46112
	ds_read_b64_tr_b16 v[210:211], v174 offset:50720
	s_waitcnt lgkmcnt(12)
	v_mfma_f32_16x16x32_bf16 v[52:55], v[240:243], v[120:123], v[52:55]
	v_mfma_f32_16x16x32_bf16 v[60:63], v[240:243], v[128:131], v[60:63]
	ds_read_b64_tr_b16 v[228:229], v174 offset:46144
	ds_read_b64_tr_b16 v[230:231], v174 offset:50752
	s_waitcnt lgkmcnt(12)
	v_mfma_f32_16x16x32_bf16 v[56:59], v[244:247], v[120:123], v[56:59]
	v_mfma_f32_16x16x32_bf16 v[68:71], v[244:247], v[128:131], v[68:71]
	ds_read_b64_tr_b16 v[232:233], v174 offset:46176
	ds_read_b64_tr_b16 v[234:235], v174 offset:50784
	s_waitcnt lgkmcnt(12)
	v_mfma_f32_16x16x32_bf16 v[64:67], v[248:251], v[120:123], v[64:67]
	v_mfma_f32_16x16x32_bf16 v[76:79], v[248:251], v[128:131], v[76:79]
	ds_read_b64_tr_b16 v[236:237], v174 offset:46208
	ds_read_b64_tr_b16 v[238:239], v174 offset:50816
	s_waitcnt lgkmcnt(12)
	v_mfma_f32_16x16x32_bf16 v[72:75], v[184:187], v[120:123], v[72:75]
	v_mfma_f32_16x16x32_bf16 v[80:83], v[184:187], v[128:131], v[80:83]
	ds_read_b64_tr_b16 v[240:241], v174 offset:46240
	ds_read_b64_tr_b16 v[242:243], v174 offset:50848
	s_waitcnt lgkmcnt(12)
	v_mfma_f32_16x16x32_bf16 v[84:87], v[188:191], v[120:123], v[84:87]
	v_mfma_f32_16x16x32_bf16 v[20:23], v[188:191], v[128:131], v[20:23]
	ds_read_b64_tr_b16 v[244:245], v174 offset:46272
	ds_read_b64_tr_b16 v[246:247], v174 offset:50880
	s_waitcnt lgkmcnt(12)
	v_mfma_f32_16x16x32_bf16 v[28:31], v[204:207], v[124:127], v[28:31]
	v_mfma_f32_16x16x32_bf16 v[36:39], v[204:207], v[152:155], v[36:39]
	ds_read_b64_tr_b16 v[248:249], v174 offset:46304
	ds_read_b64_tr_b16 v[250:251], v174 offset:50912
	s_waitcnt lgkmcnt(12)
	v_mfma_f32_16x16x32_bf16 v[32:35], v[208:211], v[124:127], v[32:35]
	v_mfma_f32_16x16x32_bf16 v[44:47], v[208:211], v[152:155], v[44:47]
	s_waitcnt lgkmcnt(10)
	v_mfma_f32_16x16x32_bf16 v[40:43], v[228:231], v[124:127], v[40:43]
	v_mfma_f32_16x16x32_bf16 v[48:51], v[228:231], v[152:155], v[48:51]
	s_waitcnt lgkmcnt(8)
	v_mfma_f32_16x16x32_bf16 v[52:55], v[232:235], v[124:127], v[52:55]
	v_mfma_f32_16x16x32_bf16 v[60:63], v[232:235], v[152:155], v[60:63]
	s_waitcnt lgkmcnt(6)
	v_mfma_f32_16x16x32_bf16 v[56:59], v[236:239], v[124:127], v[56:59]
	v_mfma_f32_16x16x32_bf16 v[68:71], v[236:239], v[152:155], v[68:71]
	s_waitcnt lgkmcnt(4)
	v_mfma_f32_16x16x32_bf16 v[64:67], v[240:243], v[124:127], v[64:67]
	v_mfma_f32_16x16x32_bf16 v[76:79], v[240:243], v[152:155], v[76:79]
	s_waitcnt lgkmcnt(2)
	v_mfma_f32_16x16x32_bf16 v[72:75], v[244:247], v[124:127], v[72:75]
	v_mfma_f32_16x16x32_bf16 v[80:83], v[244:247], v[152:155], v[80:83]
	s_waitcnt lgkmcnt(0)
	v_mfma_f32_16x16x32_bf16 v[84:87], v[248:251], v[124:127], v[84:87]
	v_mfma_f32_16x16x32_bf16 v[20:23], v[248:251], v[152:155], v[20:23]
	s_branch .LBB0_634
.Ld_groupA:
	v_mov_b32_e32 v28, 0
	v_mov_b32_e32 v29, 0
	v_mov_b32_e32 v30, 0
	v_mov_b32_e32 v31, 0
	v_mov_b32_e32 v32, 0
	v_mov_b32_e32 v33, 0
	v_mov_b32_e32 v34, 0
	v_mov_b32_e32 v35, 0
	v_mov_b32_e32 v40, 0
	v_mov_b32_e32 v41, 0
	v_mov_b32_e32 v42, 0
	v_mov_b32_e32 v43, 0
	v_mov_b32_e32 v52, 0
	v_mov_b32_e32 v53, 0
	v_mov_b32_e32 v54, 0
	v_mov_b32_e32 v55, 0
	v_mov_b32_e32 v56, 0
	v_mov_b32_e32 v57, 0
	v_mov_b32_e32 v58, 0
	v_mov_b32_e32 v59, 0
	v_mov_b32_e32 v64, 0
	v_mov_b32_e32 v65, 0
	v_mov_b32_e32 v66, 0
	v_mov_b32_e32 v67, 0
	v_mov_b32_e32 v72, 0
	v_mov_b32_e32 v73, 0
	v_mov_b32_e32 v74, 0
	v_mov_b32_e32 v75, 0
	v_mov_b32_e32 v84, 0
	v_mov_b32_e32 v85, 0
	v_mov_b32_e32 v86, 0
	v_mov_b32_e32 v87, 0
	v_mov_b32_e32 v36, 0
	v_mov_b32_e32 v37, 0
	v_mov_b32_e32 v38, 0
	v_mov_b32_e32 v39, 0
	v_mov_b32_e32 v44, 0
	v_mov_b32_e32 v45, 0
	v_mov_b32_e32 v46, 0
	v_mov_b32_e32 v47, 0
	v_mov_b32_e32 v48, 0
	v_mov_b32_e32 v49, 0
	v_mov_b32_e32 v50, 0
	v_mov_b32_e32 v51, 0
	v_mov_b32_e32 v60, 0
	v_mov_b32_e32 v61, 0
	v_mov_b32_e32 v62, 0
	v_mov_b32_e32 v63, 0
	v_mov_b32_e32 v68, 0
	v_mov_b32_e32 v69, 0
	v_mov_b32_e32 v70, 0
	v_mov_b32_e32 v71, 0
	v_mov_b32_e32 v76, 0
	v_mov_b32_e32 v77, 0
	v_mov_b32_e32 v78, 0
	v_mov_b32_e32 v79, 0
	v_mov_b32_e32 v80, 0
	v_mov_b32_e32 v81, 0
	v_mov_b32_e32 v82, 0
	v_mov_b32_e32 v83, 0
	v_mov_b32_e32 v20, 0
	v_mov_b32_e32 v21, 0
	v_mov_b32_e32 v22, 0
	v_mov_b32_e32 v23, 0
	v_mov_b32_e32 v120, 0
	v_mov_b32_e32 v121, 0
	v_mov_b32_e32 v122, 0
	v_mov_b32_e32 v123, 0
	v_mov_b32_e32 v124, 0
	v_mov_b32_e32 v125, 0
	v_mov_b32_e32 v126, 0
	v_mov_b32_e32 v127, 0
	v_mov_b32_e32 v128, 0
	v_mov_b32_e32 v129, 0
	v_mov_b32_e32 v130, 0
	v_mov_b32_e32 v131, 0
	v_mov_b32_e32 v152, 0
	v_mov_b32_e32 v153, 0
	v_mov_b32_e32 v154, 0
	v_mov_b32_e32 v155, 0
	v_mov_b32_e32 v0, 0
	v_mov_b32_e32 v151, 0
	v_mov_b32_e32 v24, 0xf149f2ca
	v_mov_b32_e32 v25, 0xf149f2ca
	v_add_u32_e32 v255, v171, v172
	v_mov_b32_e32 v165, v170
	s_mov_b32 s5, 0
	s_mov_b32 s31, 0
	s_mov_b32 s38, 0
	s_mov_b32 s39, 0x4800
	s_mov_b32 s30, 0xf8000
	v_mul_f32_e64 v156, -|v165|, v150
	v_add_f32_e32 v157, 0x3f800000, v165
	v_add_f32_e32 v158, 0x40000000, v165
	v_add_f32_e32 v159, 0x40400000, v165
	v_add_f32_e32 v160, 0x41800000, v165
	v_add_f32_e32 v161, 0x41880000, v165
	v_add_f32_e32 v162, 0x41900000, v165
	v_add_f32_e32 v163, 0x41980000, v165
	v_add_f32_e32 v176, 0x42000000, v165
	v_add_f32_e32 v177, 0x42040000, v165
	v_add_f32_e32 v178, 0x42080000, v165
	v_add_f32_e32 v179, 0x420c0000, v165
	v_add_f32_e32 v180, 0x42400000, v165
	v_add_f32_e32 v181, 0x42440000, v165
	v_add_f32_e32 v182, 0x42480000, v165
	v_add_f32_e32 v183, 0x424c0000, v165
	v_mul_f32_e64 v157, -|v157|, v150
	v_mul_f32_e64 v158, -|v158|, v150
	v_mul_f32_e64 v159, -|v159|, v150
	v_mul_f32_e64 v160, -|v160|, v150
	v_mul_f32_e64 v161, -|v161|, v150
	v_mul_f32_e64 v162, -|v162|, v150
	v_mul_f32_e64 v163, -|v163|, v150
	v_mul_f32_e64 v176, -|v176|, v150
	v_mul_f32_e64 v177, -|v177|, v150
	v_mul_f32_e64 v178, -|v178|, v150
	v_mul_f32_e64 v179, -|v179|, v150
	v_mul_f32_e64 v180, -|v180|, v150
	v_mul_f32_e64 v181, -|v181|, v150
	v_mul_f32_e64 v182, -|v182|, v150
	v_mul_f32_e64 v183, -|v183|, v150
.Ld_loopA:
	s_and_b32 s8, s5, 1
	s_mul_i32 s4, s8, 0x4800
	s_xor_b32 s8, s8, 1
	s_mul_i32 s8, s8, 0x4800
	v_add_u32_e32 v173, s4, v255
	v_add_u32_e32 v175, s8, v169
	v_add_u32_e32 v174, s31, v168
	v_add_u32_e32 v203, s38, v168
	v_add_u32_e32 v164, s39, v169
	s_mov_b32 s19, 0
	s_mov_b32 s18, s30
	v_lshl_add_u64 v[212:213], v[134:135], 0, s[18:19]
	v_lshl_add_u64 v[220:221], v[136:137], 0, s[18:19]
	s_add_u32 s18, s30, 0x7c000
	v_lshl_add_u64 v[216:217], v[134:135], 0, s[18:19]
	v_lshl_add_u64 v[224:225], v[136:137], 0, s[18:19]
	global_load_dwordx4 v[212:215], v[212:213], off
	global_load_dwordx4 v[220:223], v[220:221], off
	global_load_dwordx4 v[216:219], v[216:217], off
	global_load_dwordx4 v[224:227], v[224:225], off
	ds_read_b64_tr_b16 v[228:229], v174 offset:36864
	ds_read_b64_tr_b16 v[230:231], v174 offset:41472
	ds_read_b64_tr_b16 v[232:233], v174 offset:36896
	ds_read_b64_tr_b16 v[234:235], v174 offset:41504
	ds_read_b64_tr_b16 v[236:237], v174 offset:36928
	ds_read_b64_tr_b16 v[238:239], v174 offset:41536
	ds_read_b64_tr_b16 v[240:241], v174 offset:36960
	ds_read_b64_tr_b16 v[242:243], v174 offset:41568
	ds_read_b64_tr_b16 v[244:245], v174 offset:36992
	ds_read_b64_tr_b16 v[246:247], v174 offset:41600
	ds_read_b64_tr_b16 v[248:249], v174 offset:37024
	ds_read_b64_tr_b16 v[250:251], v174 offset:41632
	ds_read_b64_tr_b16 v[184:185], v174 offset:37056
	ds_read_b64_tr_b16 v[186:187], v174 offset:41664
	s_waitcnt lgkmcnt(12)
	v_mfma_f32_16x16x32_bf16 v[28:31], v[228:231], v[120:123], v[28:31]
	v_mfma_f32_16x16x32_bf16 v[36:39], v[228:231], v[128:131], v[36:39]
	ds_read_b64_tr_b16 v[188:189], v174 offset:37088
	ds_read_b64_tr_b16 v[190:191], v174 offset:41696
	s_waitcnt lgkmcnt(12)
	v_mfma_f32_16x16x32_bf16 v[32:35], v[232:235], v[120:123], v[32:35]
	v_mfma_f32_16x16x32_bf16 v[44:47], v[232:235], v[128:131], v[44:47]
	ds_read_b64_tr_b16 v[204:205], v174 offset:46080
	ds_read_b64_tr_b16 v[206:207], v174 offset:50688
	s_waitcnt lgkmcnt(12)
	v_mfma_f32_16x16x32_bf16 v[40:43], v[236:239], v[120:123], v[40:43]
	v_mfma_f32_16x16x32_bf16 v[48:51], v[236:239], v[128:131], v[48:51]
	ds_read_b64_tr_b16 v[208:209], v174 offset:46112
	ds_read_b64_tr_b16 v[210:211], v174 offset:50720
	s_waitcnt lgkmcnt(12)
	v_mfma_f32_16x16x32_bf16 v[52:55], v[240:243], v[120:123], v[52:55]
	v_mfma_f32_16x16x32_bf16 v[60:63], v[240:243], v[128:131], v[60:63]
	ds_read_b64_tr_b16 v[228:229], v174 offset:46144
	ds_read_b64_tr_b16 v[230:231], v174 offset:50752
	s_waitcnt lgkmcnt(12)
	v_mfma_f32_16x16x32_bf16 v[56:59], v[244:247], v[120:123], v[56:59]
	v_mfma_f32_16x16x32_bf16 v[68:71], v[244:247], v[128:131], v[68:71]
	ds_read_b64_tr_b16 v[232:233], v174 offset:46176
	ds_read_b64_tr_b16 v[234:235], v174 offset:50784
	s_waitcnt lgkmcnt(12)
	v_mfma_f32_16x16x32_bf16 v[64:67], v[248:251], v[120:123], v[64:67]
	v_mfma_f32_16x16x32_bf16 v[76:79], v[248:251], v[128:131], v[76:79]
	ds_read_b64_tr_b16 v[236:237], v174 offset:46208
	ds_read_b64_tr_b16 v[238:239], v174 offset:50816
	s_waitcnt lgkmcnt(12)
	v_mfma_f32_16x16x32_bf16 v[72:75], v[184:187], v[120:123], v[72:75]
	v_mfma_f32_16x16x32_bf16 v[80:83], v[184:187], v[128:131], v[80:83]
	ds_read_b64_tr_b16 v[240:241], v174 offset:46240
	ds_read_b64_tr_b16 v[242:243], v174 offset:50848
	s_waitcnt lgkmcnt(12)
	v_mfma_f32_16x16x32_bf16 v[84:87], v[188:191], v[120:123], v[84:87]
	v_mfma_f32_16x16x32_bf16 v[20:23], v[188:191], v[128:131], v[20:23]
	ds_read_b64_tr_b16 v[244:245], v174 offset:46272
	ds_read_b64_tr_b16 v[246:247], v174 offset:50880
	s_waitcnt lgkmcnt(12)
	v_mfma_f32_16x16x32_bf16 v[28:31], v[204:207], v[124:127], v[28:31]
	v_mfma_f32_16x16x32_bf16 v[36:39], v[204:207], v[152:155], v[36:39]
	ds_read_b64_tr_b16 v[248:249], v174 offset:46304
	ds_read_b64_tr_b16 v[250:251], v174 offset:50912
	s_waitcnt lgkmcnt(12)
	v_mfma_f32_16x16x32_bf16 v[32:35], v[208:211], v[124:127], v[32:35]
	v_mfma_f32_16x16x32_bf16 v[44:47], v[208:211], v[152:155], v[44:47]
	ds_read_b128 v[184:187], v173 offset:0
	s_waitcnt lgkmcnt(11)
	v_mfma_f32_16x16x32_bf16 v[40:43], v[228:231], v[124:127], v[40:43]
	v_mfma_f32_16x16x32_bf16 v[48:51], v[228:231], v[152:155], v[48:51]
	ds_read_b128 v[188:191], v173 offset:64
	s_waitcnt lgkmcnt(10)
	v_mfma_f32_16x16x32_bf16 v[52:55], v[232:235], v[124:127], v[52:55]
	v_mfma_f32_16x16x32_bf16 v[60:63], v[232:235], v[152:155], v[60:63]
	ds_read_b128 v[204:207], v173 offset:4608
	s_waitcnt lgkmcnt(9)
	v_mfma_f32_16x16x32_bf16 v[56:59], v[236:239], v[124:127], v[56:59]
	v_mfma_f32_16x16x32_bf16 v[68:71], v[236:239], v[152:155], v[68:71]
	ds_read_b128 v[208:211], v173 offset:4672
	s_waitcnt lgkmcnt(8)
	v_mfma_f32_16x16x32_bf16 v[64:67], v[240:243], v[124:127], v[64:67]
	v_mfma_f32_16x16x32_bf16 v[76:79], v[240:243], v[152:155], v[76:79]
	ds_read_b128 v[228:231], v173 offset:9216
	s_waitcnt lgkmcnt(7)
	v_mfma_f32_16x16x32_bf16 v[72:75], v[244:247], v[124:127], v[72:75]
	v_mfma_f32_16x16x32_bf16 v[80:83], v[244:247], v[152:155], v[80:83]
	ds_read_b128 v[232:235], v173 offset:9280
	s_waitcnt lgkmcnt(6)
	v_mfma_f32_16x16x32_bf16 v[84:87], v[248:251], v[124:127], v[84:87]
	v_mfma_f32_16x16x32_bf16 v[20:23], v[248:251], v[152:155], v[20:23]
	ds_read_b128 v[236:239], v173 offset:13824
	s_waitcnt lgkmcnt(6)
	v_mfma_f32_16x16x32_bf16 v[88:91], v[184:187], v[4:7], v[156:159]
	ds_read_b128 v[240:243], v173 offset:13888
	s_waitcnt lgkmcnt(6)
	v_mfma_f32_16x16x32_bf16 v[88:91], v[188:191], v[8:11], v[88:91]
	ds_read_b128 v[244:247], v173 offset:128
	s_waitcnt lgkmcnt(6)
	v_mfma_f32_16x16x32_bf16 v[92:95], v[204:207], v[4:7], v[160:163]
	ds_read_b128 v[248:251], v173 offset:192
	s_waitcnt lgkmcnt(6)
	v_mfma_f32_16x16x32_bf16 v[92:95], v[208:211], v[8:11], v[92:95]
	ds_read_b128 v[184:187], v173 offset:4736
	s_waitcnt lgkmcnt(6)
	v_mfma_f32_16x16x32_bf16 v[96:99], v[228:231], v[4:7], v[176:179]
	ds_read_b128 v[188:191], v173 offset:4800
	s_waitcnt lgkmcnt(6)
	v_mfma_f32_16x16x32_bf16 v[96:99], v[232:235], v[8:11], v[96:99]
	ds_read_b128 v[204:207], v173 offset:9344
	s_waitcnt lgkmcnt(6)
	v_mfma_f32_16x16x32_bf16 v[100:103], v[236:239], v[4:7], v[180:183]
	ds_read_b128 v[208:211], v173 offset:9408
	s_waitcnt lgkmcnt(6)
	v_mfma_f32_16x16x32_bf16 v[100:103], v[240:243], v[8:11], v[100:103]
	ds_read_b128 v[228:231], v173 offset:13952
	s_waitcnt lgkmcnt(6)
	v_mfma_f32_16x16x32_bf16 v[104:107], v[244:247], v[12:15], v[156:159]
	ds_read_b128 v[232:235], v173 offset:14016
	s_waitcnt lgkmcnt(6)
	v_mfma_f32_16x16x32_bf16 v[104:107], v[248:251], v[16:19], v[104:107]
	s_waitcnt lgkmcnt(5)
	v_mfma_f32_16x16x32_bf16 v[108:111], v[184:187], v[12:15], v[160:163]
	s_waitcnt lgkmcnt(4)
	v_mfma_f32_16x16x32_bf16 v[108:111], v[188:191], v[16:19], v[108:111]
	s_waitcnt lgkmcnt(3)
	v_mfma_f32_16x16x32_bf16 v[112:115], v[204:207], v[12:15], v[176:179]
	s_waitcnt lgkmcnt(2)
	v_mfma_f32_16x16x32_bf16 v[112:115], v[208:211], v[16:19], v[112:115]
	s_waitcnt lgkmcnt(1)
	v_mfma_f32_16x16x32_bf16 v[116:119], v[228:231], v[12:15], v[180:183]
	s_waitcnt lgkmcnt(0)
	v_mfma_f32_16x16x32_bf16 v[116:119], v[232:235], v[16:19], v[116:119]
	v_max3_f32 v26, v88, v89, v90
	v_max3_f32 v26, v26, v91, v92
	v_max3_f32 v26, v26, v93, v94
	v_max3_f32 v26, v26, v95, v96
	v_max3_f32 v26, v26, v97, v98
	v_max3_f32 v26, v26, v99, v100
	v_max3_f32 v26, v26, v101, v102
	v_max_f32_e32 v26, v26, v103
	v_mov_b32_e32 v27, v26
	s_nop 1
	v_permlane16_swap_b32_e32 v26, v27
	v_max_f32_e32 v26, v26, v27
	v_mov_b32_e32 v27, v26
	s_nop 1
	v_permlane32_swap_b32_e32 v26, v27
	v_max3_f32 v2, v24, v26, v27
	v_cmp_gt_f32_e32 vcc, v2, v24
	s_cbranch_vccz .Ld_nr_A_0
	v_sub_f32_e32 v3, v24, v2
	v_exp_f32_e32 v3, v3
	v_mov_b32_e32 v24, v2
	v_mul_f32_e32 v0, v0, v3
	v_mul_f32_e32 v28, v28, v3
	v_mul_f32_e32 v29, v29, v3
	v_mul_f32_e32 v30, v30, v3
	v_mul_f32_e32 v31, v31, v3
	v_mul_f32_e32 v32, v32, v3
	v_mul_f32_e32 v33, v33, v3
	v_mul_f32_e32 v34, v34, v3
	v_mul_f32_e32 v35, v35, v3
	v_mul_f32_e32 v40, v40, v3
	v_mul_f32_e32 v41, v41, v3
	v_mul_f32_e32 v42, v42, v3
	v_mul_f32_e32 v43, v43, v3
	v_mul_f32_e32 v52, v52, v3
	v_mul_f32_e32 v53, v53, v3
	v_mul_f32_e32 v54, v54, v3
	v_mul_f32_e32 v55, v55, v3
	v_mul_f32_e32 v56, v56, v3
	v_mul_f32_e32 v57, v57, v3
	v_mul_f32_e32 v58, v58, v3
	v_mul_f32_e32 v59, v59, v3
	v_mul_f32_e32 v64, v64, v3
	v_mul_f32_e32 v65, v65, v3
	v_mul_f32_e32 v66, v66, v3
	v_mul_f32_e32 v67, v67, v3
	v_mul_f32_e32 v72, v72, v3
	v_mul_f32_e32 v73, v73, v3
	v_mul_f32_e32 v74, v74, v3
	v_mul_f32_e32 v75, v75, v3
	v_mul_f32_e32 v84, v84, v3
	v_mul_f32_e32 v85, v85, v3
	v_mul_f32_e32 v86, v86, v3
	v_mul_f32_e32 v87, v87, v3

.Ld_nr_A_1:
	v_sub_f32_e32 v104, v104, v2
	v_sub_f32_e32 v105, v105, v2
	v_sub_f32_e32 v106, v106, v2
	v_sub_f32_e32 v107, v107, v2
	v_sub_f32_e32 v108, v108, v2
	v_sub_f32_e32 v109, v109, v2
	v_sub_f32_e32 v110, v110, v2
	v_sub_f32_e32 v111, v111, v2
	v_sub_f32_e32 v112, v112, v2
	v_sub_f32_e32 v113, v113, v2
	v_sub_f32_e32 v114, v114, v2
	v_sub_f32_e32 v115, v115, v2
	v_sub_f32_e32 v116, v116, v2
	v_sub_f32_e32 v117, v117, v2
	v_sub_f32_e32 v118, v118, v2
	v_sub_f32_e32 v119, v119, v2
	v_exp_f32_e32 v104, v104
	v_exp_f32_e32 v105, v105
	v_exp_f32_e32 v106, v106
	v_exp_f32_e32 v107, v107
	v_exp_f32_e32 v108, v108
	v_exp_f32_e32 v109, v109
	v_exp_f32_e32 v110, v110
	v_exp_f32_e32 v111, v111
	v_exp_f32_e32 v112, v112
	v_exp_f32_e32 v113, v113
	v_exp_f32_e32 v114, v114
	v_exp_f32_e32 v115, v115
	v_exp_f32_e32 v116, v116
	v_exp_f32_e32 v117, v117
	v_exp_f32_e32 v118, v118
	v_exp_f32_e32 v119, v119
	s_nop 0
	v_add_f32_e32 v26, v104, v105
	v_add_f32_e32 v26, v26, v106
	v_add_f32_e32 v26, v26, v107
	v_add_f32_e32 v26, v26, v108
	v_add_f32_e32 v26, v26, v109
	v_add_f32_e32 v26, v26, v110
	v_add_f32_e32 v26, v26, v111
	v_add_f32_e32 v26, v26, v112
	v_add_f32_e32 v26, v26, v113
	v_add_f32_e32 v26, v26, v114
	v_add_f32_e32 v26, v26, v115
	v_add_f32_e32 v26, v26, v116
	v_add_f32_e32 v26, v26, v117
	v_add_f32_e32 v26, v26, v118
	v_add_f32_e32 v26, v26, v119
	v_add_f32_e32 v151, v151, v26
	v_cvt_pk_bf16_f32 v128, v104, v105
	v_cvt_pk_bf16_f32 v129, v106, v107
	v_cvt_pk_bf16_f32 v130, v108, v109
	v_cvt_pk_bf16_f32 v131, v110, v111
	v_cvt_pk_bf16_f32 v152, v112, v113
	v_cvt_pk_bf16_f32 v153, v114, v115
	v_cvt_pk_bf16_f32 v154, v116, v117
	v_cvt_pk_bf16_f32 v155, v118, v119
	v_add_f32_e32 v165, 0x42800000, v165
	v_mul_f32_e64 v156, -|v165|, v150
	v_add_f32_e32 v157, 0x3f800000, v165
	v_add_f32_e32 v158, 0x40000000, v165
	v_add_f32_e32 v159, 0x40400000, v165
	v_add_f32_e32 v160, 0x41800000, v165
	v_add_f32_e32 v161, 0x41880000, v165
	v_add_f32_e32 v162, 0x41900000, v165
	v_add_f32_e32 v163, 0x41980000, v165
	v_add_f32_e32 v176, 0x42000000, v165
	v_add_f32_e32 v177, 0x42040000, v165
	v_add_f32_e32 v178, 0x42080000, v165
	v_add_f32_e32 v179, 0x420c0000, v165
	v_add_f32_e32 v180, 0x42400000, v165
	v_add_f32_e32 v181, 0x42440000, v165
	v_add_f32_e32 v182, 0x42480000, v165
	v_add_f32_e32 v183, 0x424c0000, v165
	v_mul_f32_e64 v157, -|v157|, v150
	v_mul_f32_e64 v158, -|v158|, v150
	v_mul_f32_e64 v159, -|v159|, v150
	v_mul_f32_e64 v160, -|v160|, v150
	v_mul_f32_e64 v161, -|v161|, v150
	v_mul_f32_e64 v162, -|v162|, v150
	v_mul_f32_e64 v163, -|v163|, v150
	v_mul_f32_e64 v176, -|v176|, v150
	v_mul_f32_e64 v177, -|v177|, v150
	v_mul_f32_e64 v178, -|v178|, v150
	v_mul_f32_e64 v179, -|v179|, v150
	v_mul_f32_e64 v180, -|v180|, v150
	v_mul_f32_e64 v181, -|v181|, v150
	v_mul_f32_e64 v182, -|v182|, v150
	v_mul_f32_e64 v183, -|v183|, v150
	s_waitcnt vmcnt(0)
	ds_write_b128 v175, v[212:215]
	ds_write_b128 v175, v[216:219] offset:9216
	ds_write_b128 v164, v[220:223] offset:36864
	ds_write_b128 v164, v[224:227] offset:46080
	s_mov_b32 s31, s38
	s_mov_b32 s38, s39
	s_add_i32 s39, s39, 0x4800
	s_cmp_lg_u32 s39, 0xd800
	s_cselect_b32 s39, s39, 0
	s_add_i32 s5, s5, 1
	s_min_u32 s8, s5, 62
	s_add_i32 s8, s8, 1
	s_mul_i32 s30, s8, 0xf8000
	s_waitcnt lgkmcnt(0)
	s_barrier
	s_cmp_lt_u32 s5, 64
	s_cbranch_scc1 .Ld_loopA
	v_add_u32_e32 v174, s31, v168
	ds_read_b64_tr_b16 v[228:229], v174 offset:36864
	ds_read_b64_tr_b16 v[230:231], v174 offset:41472
	ds_read_b64_tr_b16 v[232:233], v174 offset:36896
	ds_read_b64_tr_b16 v[234:235], v174 offset:41504
	ds_read_b64_tr_b16 v[236:237], v174 offset:36928
	ds_read_b64_tr_b16 v[238:239], v174 offset:41536
	ds_read_b64_tr_b16 v[240:241], v174 offset:36960
	ds_read_b64_tr_b16 v[242:243], v174 offset:41568
	ds_read_b64_tr_b16 v[244:245], v174 offset:36992
	ds_read_b64_tr_b16 v[246:247], v174 offset:41600
	ds_read_b64_tr_b16 v[248:249], v174 offset:37024
	ds_read_b64_tr_b16 v[250:251], v174 offset:41632
	ds_read_b64_tr_b16 v[184:185], v174 offset:37056
	ds_read_b64_tr_b16 v[186:187], v174 offset:41664
	s_waitcnt lgkmcnt(12)
	v_mfma_f32_16x16x32_bf16 v[28:31], v[228:231], v[120:123], v[28:31]
	v_mfma_f32_16x16x32_bf16 v[36:39], v[228:231], v[128:131], v[36:39]
	ds_read_b64_tr_b16 v[188:189], v174 offset:37088
	ds_read_b64_tr_b16 v[190:191], v174 offset:41696
	s_waitcnt lgkmcnt(12)
	v_mfma_f32_16x16x32_bf16 v[32:35], v[232:235], v[120:123], v[32:35]
	v_mfma_f32_16x16x32_bf16 v[44:47], v[232:235], v[128:131], v[44:47]
	ds_read_b64_tr_b16 v[204:205], v174 offset:46080
	ds_read_b64_tr_b16 v[206:207], v174 offset:50688
	s_waitcnt lgkmcnt(12)
	v_mfma_f32_16x16x32_bf16 v[40:43], v[236:239], v[120:123], v[40:43]
	v_mfma_f32_16x16x32_bf16 v[48:51], v[236:239], v[128:131], v[48:51]
	ds_read_b64_tr_b16 v[208:209], v174 offset:46112
	ds_read_b64_tr_b16 v[210:211], v174 offset:50720
	s_waitcnt lgkmcnt(12)
	v_mfma_f32_16x16x32_bf16 v[52:55], v[240:243], v[120:123], v[52:55]
	v_mfma_f32_16x16x32_bf16 v[60:63], v[240:243], v[128:131], v[60:63]
	ds_read_b64_tr_b16 v[228:229], v174 offset:46144
	ds_read_b64_tr_b16 v[230:231], v174 offset:50752
	s_waitcnt lgkmcnt(12)
	v_mfma_f32_16x16x32_bf16 v[56:59], v[244:247], v[120:123], v[56:59]
	v_mfma_f32_16x16x32_bf16 v[68:71], v[244:247], v[128:131], v[68:71]
	ds_read_b64_tr_b16 v[232:233], v174 offset:46176
	ds_read_b64_tr_b16 v[234:235], v174 offset:50784
	s_waitcnt lgkmcnt(12)
	v_mfma_f32_16x16x32_bf16 v[64:67], v[248:251], v[120:123], v[64:67]
	v_mfma_f32_16x16x32_bf16 v[76:79], v[248:251], v[128:131], v[76:79]
	ds_read_b64_tr_b16 v[236:237], v174 offset:46208
	ds_read_b64_tr_b16 v[238:239], v174 offset:50816
	s_waitcnt lgkmcnt(12)
	v_mfma_f32_16x16x32_bf16 v[72:75], v[184:187], v[120:123], v[72:75]
	v_mfma_f32_16x16x32_bf16 v[80:83], v[184:187], v[128:131], v[80:83]
	ds_read_b64_tr_b16 v[240:241], v174 offset:46240
	ds_read_b64_tr_b16 v[242:243], v174 offset:50848
	s_waitcnt lgkmcnt(12)
	v_mfma_f32_16x16x32_bf16 v[84:87], v[188:191], v[120:123], v[84:87]
	v_mfma_f32_16x16x32_bf16 v[20:23], v[188:191], v[128:131], v[20:23]
	ds_read_b64_tr_b16 v[244:245], v174 offset:46272
	ds_read_b64_tr_b16 v[246:247], v174 offset:50880
	s_waitcnt lgkmcnt(12)
	v_mfma_f32_16x16x32_bf16 v[28:31], v[204:207], v[124:127], v[28:31]
	v_mfma_f32_16x16x32_bf16 v[36:39], v[204:207], v[152:155], v[36:39]
	ds_read_b64_tr_b16 v[248:249], v174 offset:46304
	ds_read_b64_tr_b16 v[250:251], v174 offset:50912
	s_waitcnt lgkmcnt(12)
	v_mfma_f32_16x16x32_bf16 v[32:35], v[208:211], v[124:127], v[32:35]
	v_mfma_f32_16x16x32_bf16 v[44:47], v[208:211], v[152:155], v[44:47]
	s_waitcnt lgkmcnt(10)
	v_mfma_f32_16x16x32_bf16 v[40:43], v[228:231], v[124:127], v[40:43]
	v_mfma_f32_16x16x32_bf16 v[48:51], v[228:231], v[152:155], v[48:51]
	s_waitcnt lgkmcnt(8)
	v_mfma_f32_16x16x32_bf16 v[52:55], v[232:235], v[124:127], v[52:55]
	v_mfma_f32_16x16x32_bf16 v[60:63], v[232:235], v[152:155], v[60:63]
	s_waitcnt lgkmcnt(6)
	v_mfma_f32_16x16x32_bf16 v[56:59], v[236:239], v[124:127], v[56:59]
	v_mfma_f32_16x16x32_bf16 v[68:71], v[236:239], v[152:155], v[68:71]
	s_waitcnt lgkmcnt(4)
	v_mfma_f32_16x16x32_bf16 v[64:67], v[240:243], v[124:127], v[64:67]
	v_mfma_f32_16x16x32_bf16 v[76:79], v[240:243], v[152:155], v[76:79]
	s_waitcnt lgkmcnt(2)
	v_mfma_f32_16x16x32_bf16 v[72:75], v[244:247], v[124:127], v[72:75]
	v_mfma_f32_16x16x32_bf16 v[80:83], v[244:247], v[152:155], v[80:83]
	s_waitcnt lgkmcnt(0)
	v_mfma_f32_16x16x32_bf16 v[84:87], v[248:251], v[124:127], v[84:87]
	v_mfma_f32_16x16x32_bf16 v[20:23], v[248:251], v[152:155], v[20:23]

	.amdhsa_kernel _Z14fwd_megakernel6Params
		.amdhsa_group_segment_fixed_size 0
		.amdhsa_private_segment_fixed_size 0
		.amdhsa_kernarg_size 464
		.amdhsa_user_sgpr_count 2
		.amdhsa_user_sgpr_dispatch_ptr 0
		.amdhsa_user_sgpr_queue_ptr 0
		.amdhsa_user_sgpr_kernarg_segment_ptr 1
		.amdhsa_user_sgpr_dispatch_id 0
		.amdhsa_user_sgpr_kernarg_preload_length 0
		.amdhsa_user_sgpr_kernarg_preload_offset 0
		.amdhsa_user_sgpr_private_segment_size 0
		.amdhsa_uses_dynamic_stack 0
		.amdhsa_enable_private_segment 0
		.amdhsa_system_sgpr_workgroup_id_x 1
		.amdhsa_system_sgpr_workgroup_id_y 0
		.amdhsa_system_sgpr_workgroup_id_z 0
		.amdhsa_system_sgpr_workgroup_info 0
		.amdhsa_system_vgpr_workitem_id 2
		.amdhsa_next_free_vgpr 256
		.amdhsa_next_free_sgpr 100
		.amdhsa_accum_offset 256
		.amdhsa_reserve_vcc 1
		.amdhsa_float_round_mode_32 0
		.amdhsa_float_round_mode_16_64 0
		.amdhsa_float_denorm_mode_32 3
		.amdhsa_float_denorm_mode_16_64 3
		.amdhsa_dx10_clamp 1
		.amdhsa_ieee_mode 1
		.amdhsa_fp16_overflow 0
		.amdhsa_tg_split 0
		.amdhsa_exception_fp_ieee_invalid_op 0
		.amdhsa_exception_fp_denorm_src 0
		.amdhsa_exception_fp_ieee_div_zero 0
		.amdhsa_exception_fp_ieee_overflow 0
		.amdhsa_exception_fp_ieee_underflow 0
		.amdhsa_exception_fp_ieee_inexact 0
		.amdhsa_exception_int_div_zero 0
	.end_amdhsa_kernel

amdhsa.kernels:
  - .agpr_count:     0
    .args:
      - .offset:         0
        .size:           208
        .value_kind:     by_value
      - .offset:         208
        .size:           4
        .value_kind:     hidden_block_count_x
      - .offset:         212
        .size:           4
        .value_kind:     hidden_block_count_y
      - .offset:         216
        .size:           4
        .value_kind:     hidden_block_count_z
      - .offset:         220
        .size:           2
        .value_kind:     hidden_group_size_x
      - .offset:         222
        .size:           2
        .value_kind:     hidden_group_size_y
      - .offset:         224
        .size:           2
        .value_kind:     hidden_group_size_z
      - .offset:         226
        .size:           2
        .value_kind:     hidden_remainder_x
      - .offset:         228
        .size:           2
        .value_kind:     hidden_remainder_y
      - .offset:         230
        .size:           2
        .value_kind:     hidden_remainder_z
      - .offset:         248
        .size:           8
        .value_kind:     hidden_global_offset_x
      - .offset:         256
        .size:           8
        .value_kind:     hidden_global_offset_y
      - .offset:         264
        .size:           8
        .value_kind:     hidden_global_offset_z
      - .offset:         272
        .size:           2
        .value_kind:     hidden_grid_dims
      - .offset:         296
        .size:           8
        .value_kind:     hidden_multigrid_sync_arg
      - .offset:         328
        .size:           4
        .value_kind:     hidden_dynamic_lds_size
    .group_segment_fixed_size: 0
    .kernarg_segment_align: 8
    .kernarg_segment_size: 464
    .language:       OpenCL C
    .language_version:
      - 2
      - 0
    .max_flat_workgroup_size: 512
    .name:           _Z14fwd_megakernel6Params
    .private_segment_fixed_size: 0
    .sgpr_count:     106
    .sgpr_spill_count: 133
    .symbol:         _Z14fwd_megakernel6Params.kd
    .uniform_work_group_size: 1
    .uses_dynamic_stack: false
    .vgpr_count:     256
    .vgpr_spill_count: 0
    .wavefront_size: 64
